# grid-barrier poll interval: s_sleep 1 replaced by s_nop 7 in the ten polling loops
# baseline (speedup 1.0000x reference)
; __device__ __forceinline__ unsigned xb_ld(unsigned* p)              { return __hip_atomic_load(p, __ATOMIC_RELAXED, __HIP_MEMORY_SCOPE_AGENT); }
; __device__ __forceinline__ void xcd_barrier_complete(unsigned* bar, unsigned x, unsigned& nloc, unsigned& nx) {
;     ...
;     for (;;) {
;         sum = 0u; cnt = 0u; mine = 0u;
; #pragma unroll
;         for (unsigned j = 0; j < 16; ++j) { const unsigned c = xb_ld(&bar[XB_XCNT(j)]); sum += c; cnt += (c > 0u) ? 1u : 0u; mine = (j == x) ? c : mine; }
;         if (sum == G) break;
;         __builtin_amdgcn_s_sleep(1);
;         if ((++sp & 255u) == 0u) { if (xb_ld(&bar[XB_TMO])) break; if (sp > XB_SPIN_CAP) { atomicAdd(&bar[XB_TMO], 1u); break; } }
.LBB0_893:
	v_readlane_b32 s8, v251, 34
	v_readlane_b32 s9, v251, 35
	s_mov_b64 s[10:11], -1
	s_nop 3
	global_load_dword v0, v165, s[8:9] sc1
	global_load_dword v1, v165, s[8:9] offset:256 sc1
	global_load_dword v2, v165, s[8:9] offset:512 sc1
	global_load_dword v3, v165, s[8:9] offset:768 sc1
	global_load_dword v4, v165, s[8:9] offset:1024 sc1
	global_load_dword v5, v165, s[8:9] offset:1280 sc1
	global_load_dword v6, v165, s[8:9] offset:1536 sc1
	global_load_dword v7, v165, s[8:9] offset:1792 sc1
	global_load_dword v8, v165, s[8:9] offset:2048 sc1
	global_load_dword v9, v165, s[8:9] offset:2304 sc1
	global_load_dword v10, v165, s[8:9] offset:2560 sc1
	global_load_dword v11, v165, s[8:9] offset:2816 sc1
	global_load_dword v12, v165, s[8:9] offset:3072 sc1
	global_load_dword v13, v165, s[8:9] offset:3328 sc1
	global_load_dword v14, v165, s[8:9] offset:3584 sc1
	global_load_dword v15, v165, s[8:9] offset:3840 sc1
	s_mov_b64 s[8:9], -1
	s_waitcnt vmcnt(0)
	v_add_u32_e32 v16, v1, v0
	v_add_u32_e32 v16, v16, v2
	v_add_u32_e32 v16, v16, v3
	v_add_u32_e32 v16, v16, v4
	v_add_u32_e32 v16, v16, v5
	v_add_u32_e32 v16, v16, v6
	v_add_u32_e32 v16, v16, v7
	v_add_u32_e32 v16, v16, v8
	v_add_u32_e32 v16, v16, v9
	v_add_u32_e32 v16, v16, v10
	v_add_u32_e32 v16, v16, v11
	v_add_u32_e32 v16, v16, v12
	v_add_u32_e32 v16, v16, v13
	v_add_u32_e32 v16, v16, v14
	v_add_u32_e32 v16, v16, v15
	v_cmp_eq_u32_e32 vcc, s6, v16
	s_cbranch_vccnz .LBB0_892
	s_and_b32 s8, s7, 0xff
	s_cmp_eq_u32 s8, 0
	s_mov_b64 s[8:9], -1
	s_mov_b64 s[12:13], -1
	s_nop 7
	s_cbranch_scc1 .LBB0_897
	s_and_b64 vcc, exec, s[12:13]
	s_cbranch_vccz .LBB0_892

.LBB0_909:
	s_and_b32 s7, s6, 0xff
	s_mov_b64 s[20:21], -1
	s_cmp_lg_u32 s7, 0
	s_mov_b64 s[24:25], -1
	s_nop 7
	s_cbranch_scc0 .LBB0_912
	s_and_b64 vcc, exec, s[24:25]
	s_cbranch_vccz .LBB0_908

.LBB0_926:
	s_and_b32 s7, s6, 0xff
	s_mov_b64 s[18:19], -1
	s_cmp_lg_u32 s7, 0
	s_mov_b64 s[22:23], -1
	s_nop 7
	s_cbranch_scc0 .LBB0_929
	s_and_b64 vcc, exec, s[22:23]
	s_cbranch_vccz .LBB0_925

; __global__ void __launch_bounds__(NWAVES * 64) mega(Args a) {
;     ...
;         if (p + 1 < a.ph_hi) { if (p == a.ph_lo) { cg::this_grid().sync(); xbar = xcd_barrier_post((unsigned*)(ws + WS_BAR), bst); } else xcd_barrier(xbar); if (a.sub & 256) xcd_barrier(xbar); if (a.sub & 512) xcd_barrier_v<false, false>(xbar); }
.LBB0_947:
	s_nop 7
	global_load_dword v1, v165, s[8:9] offset:32 sc1
	s_waitcnt vmcnt(0)
	v_and_b32_e32 v1, 0xffff0000, v1
	v_cmp_ne_u32_e32 vcc, v1, v0
	s_or_b64 s[10:11], vcc, s[10:11]
	s_andn2_b64 exec, exec, s[10:11]
	s_cbranch_execnz .LBB0_947

; __device__ __forceinline__ unsigned xb_ld(unsigned* p)              { return __hip_atomic_load(p, __ATOMIC_RELAXED, __HIP_MEMORY_SCOPE_AGENT); }
; __device__ __forceinline__ void xcd_barrier_complete(unsigned* bar, unsigned x, unsigned& nloc, unsigned& nx) {
;     ...
;     for (;;) {
;         sum = 0u; cnt = 0u; mine = 0u;
; #pragma unroll
;         for (unsigned j = 0; j < 16; ++j) { const unsigned c = xb_ld(&bar[XB_XCNT(j)]); sum += c; cnt += (c > 0u) ? 1u : 0u; mine = (j == x) ? c : mine; }
;         if (sum == G) break;
;         __builtin_amdgcn_s_sleep(1);
;         if ((++sp & 255u) == 0u) { if (xb_ld(&bar[XB_TMO])) break; if (sp > XB_SPIN_CAP) { atomicAdd(&bar[XB_TMO], 1u); break; } }
.LBB0_958:
	v_readlane_b32 s8, v251, 34
	v_readlane_b32 s9, v251, 35
	s_mov_b64 s[10:11], -1
	s_nop 3
	global_load_dword v0, v165, s[8:9] sc1
	v_readlane_b32 s8, v251, 36
	v_readlane_b32 s9, v251, 37
	s_nop 4
	global_load_dword v1, v165, s[8:9] sc1
	v_readlane_b32 s8, v251, 38
	v_readlane_b32 s9, v251, 39
	s_waitcnt vmcnt(0)
	v_add_u32_e32 v16, v1, v0
	s_nop 2
	global_load_dword v2, v165, s[8:9] sc1
	v_readlane_b32 s8, v251, 40
	v_readlane_b32 s9, v251, 41
	s_waitcnt vmcnt(0)
	v_add_u32_e32 v16, v16, v2
	s_nop 2
	global_load_dword v3, v165, s[8:9] sc1
	v_readlane_b32 s8, v251, 42
	v_readlane_b32 s9, v251, 43
	s_waitcnt vmcnt(0)
	v_add_u32_e32 v16, v16, v3
	s_nop 2
	global_load_dword v4, v165, s[8:9] sc1
	v_readlane_b32 s8, v251, 44
	v_readlane_b32 s9, v251, 45
	s_waitcnt vmcnt(0)
	v_add_u32_e32 v16, v16, v4
	s_nop 2
	global_load_dword v5, v165, s[8:9] sc1
	v_readlane_b32 s8, v251, 46
	v_readlane_b32 s9, v251, 47
	s_waitcnt vmcnt(0)
	v_add_u32_e32 v16, v16, v5
	s_nop 2
	global_load_dword v6, v165, s[8:9] sc1
	v_readlane_b32 s8, v251, 48
	v_readlane_b32 s9, v251, 49
	s_waitcnt vmcnt(0)
	v_add_u32_e32 v16, v16, v6
	s_nop 2
	global_load_dword v7, v165, s[8:9] sc1
	v_readlane_b32 s8, v251, 50
	v_readlane_b32 s9, v251, 51
	s_waitcnt vmcnt(0)
	v_add_u32_e32 v16, v16, v7
	s_nop 2
	global_load_dword v8, v165, s[8:9] sc1
	v_readlane_b32 s8, v251, 52
	v_readlane_b32 s9, v251, 53
	s_waitcnt vmcnt(0)
	v_add_u32_e32 v16, v16, v8
	s_nop 2
	global_load_dword v9, v165, s[8:9] sc1
	v_readlane_b32 s8, v251, 54
	v_readlane_b32 s9, v251, 55
	s_waitcnt vmcnt(0)
	v_add_u32_e32 v16, v16, v9
	s_nop 2
	global_load_dword v10, v165, s[8:9] sc1
	v_readlane_b32 s8, v251, 56
	v_readlane_b32 s9, v251, 57
	s_waitcnt vmcnt(0)
	v_add_u32_e32 v16, v16, v10
	s_nop 2
	global_load_dword v11, v165, s[8:9] sc1
	v_readlane_b32 s8, v251, 58
	v_readlane_b32 s9, v251, 59
	s_waitcnt vmcnt(0)
	v_add_u32_e32 v16, v16, v11
	s_nop 2
	global_load_dword v12, v165, s[8:9] sc1
	v_readlane_b32 s8, v251, 60
	v_readlane_b32 s9, v251, 61
	s_waitcnt vmcnt(0)
	v_add_u32_e32 v16, v16, v12
	s_nop 2
	global_load_dword v13, v165, s[8:9] sc1
	v_readlane_b32 s8, v251, 62
	v_readlane_b32 s9, v251, 63
	s_waitcnt vmcnt(0)
	v_add_u32_e32 v16, v16, v13
	s_nop 2
	global_load_dword v14, v165, s[8:9] sc1
	v_readlane_b32 s8, v252, 0
	v_readlane_b32 s9, v252, 1
	s_waitcnt vmcnt(0)
	v_add_u32_e32 v16, v16, v14
	s_nop 2
	global_load_dword v15, v165, s[8:9] sc1
	s_mov_b64 s[8:9], -1
	s_waitcnt vmcnt(0)
	v_add_u32_e32 v16, v16, v15
	v_cmp_eq_u32_e32 vcc, s6, v16
	s_cbranch_vccnz .LBB0_957
	s_and_b32 s8, s7, 0xff
	s_cmp_eq_u32 s8, 0
	s_mov_b64 s[8:9], -1
	s_mov_b64 s[12:13], -1
	s_nop 7
	s_cbranch_scc1 .LBB0_962
	s_and_b64 vcc, exec, s[12:13]
	s_cbranch_vccz .LBB0_957
